# one static s_setprio 1 for waves 4-7 at kernel start, all per-phase flips deleted (strategy 4 static form)
# baseline (speedup 1.0000x reference)
; #define LAS __attribute__((address_space(3)))
; __device__ __forceinline__ unsigned xb_add(unsigned* p, unsigned v) { return __hip_atomic_fetch_add(p, v, __ATOMIC_RELAXED, __HIP_MEMORY_SCOPE_AGENT); }
; __device__ __forceinline__ unsigned xb_xcc_id() { return (unsigned)__builtin_amdgcn_s_getreg((3 << 11) | 20) & 0xFu; }
; __device__ __forceinline__ XcdBarrier xcd_barrier_post(unsigned* bar, volatile LAS unsigned* st) {
;     XcdBarrier b; b.bar = bar; b.x = xb_xcc_id(); b.st = st;
;     if (threadIdx.x == 0) (void)xb_add(&bar[XB_XCNT(b.x)], 1u);
;     return b;
; __global__ void __launch_bounds__(NTHREADS, 2) fwd_megakernel(Args a) {
;     ...
;     cg::grid_group grid = cg::this_grid();
;     volatile LAS unsigned* bst = (volatile LAS unsigned*)(lds + LDS_BYTES - 16);
;     if (threadIdx.x < 4) bst[threadIdx.x] = 0u;
;     __syncthreads();
;     XcdBarrier xbar = xcd_barrier_post((unsigned*)(a.ws + WS_BAR), bst);
_Z14fwd_megakernel4Args:
	s_load_dwordx8 s[52:59], s[0:1], 0x80
	s_load_dword s94, s[0:1], 0xa0
	s_add_u32 s6, s0, 0x98
	v_and_b32_e32 v224, 0x3ff, v0
	s_addc_u32 s7, s1, 0
	v_cmp_gt_u32_e32 vcc, 4, v224
	v_lshl_add_u32 v190, v224, 2, 0
	s_and_saveexec_b64 s[4:5], vcc
	v_add_u32_e32 v1, 0x271f0, v190
	v_mov_b32_e32 v2, 0
	ds_write_b32 v1, v2
	s_or_b64 exec, exec, s[4:5]
	s_waitcnt lgkmcnt(0)
	s_barrier
	v_readfirstlane_b32 s98, v224
	s_nop 3
	s_cmp_lt_u32 s98, 0x100
	s_cbranch_scc1 .Lprio_skip
	s_setprio 1
.Lprio_skip:
	s_add_u32 s28, s54, 0x3e400000
	s_getreg_b32 s3, hwreg(HW_REG_XCC_ID, 0, 4)
	v_cmp_eq_u32_e64 s[8:9], 0, v224
	s_addc_u32 s29, s55, 0
	s_and_b32 s3, s3, 15
	v_writelane_b32 v240, s8, 0
	s_nop 1
	v_writelane_b32 v240, s9, 1
	s_and_saveexec_b64 s[4:5], s[8:9]
	s_cbranch_execz .LBB0_5
	s_mov_b64 s[10:11], exec
	v_mbcnt_lo_u32_b32 v1, s10, 0
	v_mbcnt_hi_u32_b32 v1, s11, v1
	v_cmp_eq_u32_e32 vcc, 0, v1
	s_and_b64 s[12:13], exec, vcc
	s_mov_b64 exec, s[12:13]
	s_cbranch_execz .LBB0_5
	s_lshl_b32 s12, s3, 8
	s_bcnt1_i32_b64 s10, s[10:11]
	v_mov_b32_e32 v1, s12
	v_mov_b32_e32 v2, s10
	global_atomic_add v1, v2, s[28:29] offset:1024
